# proj GEMM: first two vmcnt waits of each tile relaxed to vmcnt(24) so the previous tile's 16 epilogue stores need not have completed
# speedup vs baseline: 1.1063x; 1.0052x over previous
.LBB0_488:
	s_ashr_i32 s25, s24, 31
	s_lshl_b64 s[4:5], s[24:25], 19
	s_add_u32 s26, s12, s4
	s_addc_u32 s27, s13, s5
	s_and_b64 s[4:5], s[40:41], exec
	s_cselect_b32 s25, s27, s31
	s_cselect_b32 s66, s26, s30
	s_ashr_i32 s23, s22, 31
	s_lshl_b64 s[4:5], s[22:23], 19
	s_add_u32 s28, s39, s4
	s_addc_u32 s29, s42, s5
	s_and_b64 s[4:5], s[40:41], exec
	s_cselect_b32 s23, s29, s35
	s_cselect_b32 s67, s28, s34
	s_add_u32 s30, s30, 0x40080
	s_addc_u32 s31, s31, 0
	s_add_u32 s68, s34, 0x100
	v_mov_b32_e32 v2, 0
	s_addc_u32 s69, s35, 0
	s_mov_b32 s59, -2
	s_add_u32 s4, s30, 0xfffc0080
	s_addc_u32 s5, s31, -1
	s_add_i32 s6, 0, 0x10000
	s_cmp_eq_u32 s59, 12
	s_cselect_b32 s37, s25, s5
	s_cselect_b32 s36, s66, s4
	s_cselect_b32 s35, s23, s69
	s_cselect_b32 s34, s67, s68
	s_add_i32 s7, 0, 0x14000
	v_add_u32_e32 v156, s6, v146
	v_add_u32_e32 v172, s7, v146
	ds_read_b128 v[140:143], v156
	ds_read_b128 v[148:151], v156 offset:1024
	ds_read_b128 v[152:155], v156 offset:2048
	ds_read_b128 v[156:159], v156 offset:3072
	ds_read_b128 v[160:163], v172
	ds_read_b128 v[164:167], v172 offset:1024
	ds_read_b128 v[168:171], v172 offset:2048
	ds_read_b128 v[172:175], v172 offset:3072
	v_lshl_add_u64 v[208:209], s[30:31], 0, v[136:137]
	s_add_i32 m0, s43, 0xc000
	ds_read_b128 v[176:179], v147
	ds_read_b128 v[180:183], v147 offset:1024
	ds_read_b128 v[184:187], v147 offset:2048
	ds_read_b128 v[188:191], v147 offset:3072
	ds_read_b128 v[192:195], v147 offset:4096
	ds_read_b128 v[196:199], v147 offset:5120
	ds_read_b128 v[200:203], v147 offset:6144
	ds_read_b128 v[204:207], v147 offset:7168
	global_load_lds_dwordx4 v[208:209], off
	v_lshl_add_u64 v[208:209], s[30:31], 0, v[138:139]
	s_add_i32 m0, s43, 0xe000
	s_nop 0
	global_load_lds_dwordx4 v[208:209], off
	s_waitcnt vmcnt(24)
	s_waitcnt lgkmcnt(0)
	s_barrier
	s_setprio 1
	s_waitcnt lgkmcnt(0)
	v_mfma_f32_16x16x32_bf16 v[126:129], v[140:143], v[176:179], 0
	v_mfma_f32_16x16x32_bf16 v[122:125], v[152:155], v[176:179], 0
	v_mfma_f32_16x16x32_bf16 v[118:121], v[140:143], v[184:187], 0
	v_mfma_f32_16x16x32_bf16 v[110:113], v[152:155], v[184:187], 0
	v_mfma_f32_16x16x32_bf16 v[102:105], v[140:143], v[192:195], 0
	v_mfma_f32_16x16x32_bf16 v[94:97], v[152:155], v[192:195], 0
	v_mfma_f32_16x16x32_bf16 v[86:89], v[140:143], v[200:203], 0
	v_mfma_f32_16x16x32_bf16 v[78:81], v[152:155], v[200:203], 0
	v_mfma_f32_16x16x32_bf16 v[126:129], v[148:151], v[180:183], v[126:129]
	v_mfma_f32_16x16x32_bf16 v[122:125], v[156:159], v[180:183], v[122:125]
	v_mfma_f32_16x16x32_bf16 v[118:121], v[148:151], v[188:191], v[118:121]
	v_mfma_f32_16x16x32_bf16 v[110:113], v[156:159], v[188:191], v[110:113]
	v_mfma_f32_16x16x32_bf16 v[102:105], v[148:151], v[196:199], v[102:105]
	v_mfma_f32_16x16x32_bf16 v[94:97], v[156:159], v[196:199], v[94:97]
	v_mfma_f32_16x16x32_bf16 v[86:89], v[148:151], v[204:207], v[86:89]
	v_mfma_f32_16x16x32_bf16 v[78:81], v[156:159], v[204:207], v[78:81]
	s_setprio 0
	s_setprio 1
	v_mfma_f32_16x16x32_bf16 v[114:117], v[160:163], v[176:179], 0
	v_mfma_f32_16x16x32_bf16 v[106:109], v[168:171], v[176:179], 0
	v_mfma_f32_16x16x32_bf16 v[98:101], v[160:163], v[184:187], 0
	v_mfma_f32_16x16x32_bf16 v[90:93], v[168:171], v[184:187], 0
	v_mfma_f32_16x16x32_bf16 v[82:85], v[160:163], v[192:195], 0
	v_mfma_f32_16x16x32_bf16 v[74:77], v[168:171], v[192:195], 0
	v_mfma_f32_16x16x32_bf16 v[70:73], v[160:163], v[200:203], 0
	v_mfma_f32_16x16x32_bf16 v[66:69], v[168:171], v[200:203], 0
	v_mfma_f32_16x16x32_bf16 v[114:117], v[164:167], v[180:183], v[114:117]
	v_mfma_f32_16x16x32_bf16 v[106:109], v[172:175], v[180:183], v[106:109]
	v_mfma_f32_16x16x32_bf16 v[98:101], v[164:167], v[188:191], v[98:101]
	v_mfma_f32_16x16x32_bf16 v[90:93], v[172:175], v[188:191], v[90:93]
	v_mfma_f32_16x16x32_bf16 v[82:85], v[164:167], v[196:199], v[82:85]
	v_mfma_f32_16x16x32_bf16 v[74:77], v[172:175], v[196:199], v[74:77]
	v_mfma_f32_16x16x32_bf16 v[70:73], v[164:167], v[204:207], v[70:73]
	s_barrier
	v_mfma_f32_16x16x32_bf16 v[66:69], v[172:175], v[204:207], v[66:69]
	s_setprio 0
	s_add_i32 s4, s6, s38
	v_lshl_add_u64 v[208:209], s[34:35], 0, v[0:1]
	s_mov_b32 m0, s4
	ds_read_b128 v[176:179], v147 offset:16384
	ds_read_b128 v[180:183], v147 offset:17408
	ds_read_b128 v[184:187], v147 offset:18432
	ds_read_b128 v[188:191], v147 offset:19456
	ds_read_b128 v[192:195], v147 offset:20480
	ds_read_b128 v[196:199], v147 offset:21504
	ds_read_b128 v[200:203], v147 offset:22528
	ds_read_b128 v[204:207], v147 offset:23552
	global_load_lds_dwordx4 v[208:209], off
	s_add_i32 m0, s4, 0x2000
	s_add_u32 s4, s34, 0x40000
	v_lshl_add_u64 v[222:223], s[34:35], 0, v[132:133]
	s_addc_u32 s5, s35, 0
	s_add_i32 s6, s7, s38
	global_load_lds_dwordx4 v[222:223], off
	v_lshl_add_u64 v[224:225], s[4:5], 0, v[0:1]
	s_mov_b32 m0, s6
	v_lshl_add_u64 v[226:227], s[36:37], 0, v[130:131]
	global_load_lds_dwordx4 v[224:225], off
	v_lshl_add_u64 v[224:225], s[4:5], 0, v[132:133]
	s_add_i32 m0, s6, 0x2000
	s_nop 0
	global_load_lds_dwordx4 v[224:225], off
	v_lshl_add_u64 v[224:225], s[36:37], 0, v[134:135]
	s_mov_b32 m0, s43
	s_nop 0
	global_load_lds_dwordx4 v[224:225], off
	s_mov_b32 m0, s44
	s_nop 0
	global_load_lds_dwordx4 v[226:227], off
	s_waitcnt vmcnt(24)
	s_waitcnt lgkmcnt(0)
	s_barrier
	s_setprio 1
	s_waitcnt lgkmcnt(0)
	v_mfma_f32_16x16x32_bf16 v[62:65], v[140:143], v[176:179], 0
	v_mfma_f32_16x16x32_bf16 v[58:61], v[152:155], v[176:179], 0
	v_mfma_f32_16x16x32_bf16 v[54:57], v[140:143], v[184:187], 0
	v_mfma_f32_16x16x32_bf16 v[46:49], v[152:155], v[184:187], 0
	v_mfma_f32_16x16x32_bf16 v[38:41], v[140:143], v[192:195], 0
	v_mfma_f32_16x16x32_bf16 v[30:33], v[152:155], v[192:195], 0
	v_mfma_f32_16x16x32_bf16 v[22:25], v[140:143], v[200:203], 0
	v_mfma_f32_16x16x32_bf16 v[14:17], v[152:155], v[200:203], 0
	v_mfma_f32_16x16x32_bf16 v[62:65], v[148:151], v[180:183], v[62:65]
	v_mfma_f32_16x16x32_bf16 v[58:61], v[156:159], v[180:183], v[58:61]
	v_mfma_f32_16x16x32_bf16 v[54:57], v[148:151], v[188:191], v[54:57]
	v_mfma_f32_16x16x32_bf16 v[46:49], v[156:159], v[188:191], v[46:49]
	v_mfma_f32_16x16x32_bf16 v[38:41], v[148:151], v[196:199], v[38:41]
	v_mfma_f32_16x16x32_bf16 v[30:33], v[156:159], v[196:199], v[30:33]
	v_mfma_f32_16x16x32_bf16 v[22:25], v[148:151], v[204:207], v[22:25]
	v_mfma_f32_16x16x32_bf16 v[14:17], v[156:159], v[204:207], v[14:17]
	s_setprio 0
	s_setprio 1
	v_mfma_f32_16x16x32_bf16 v[50:53], v[160:163], v[176:179], 0
	v_mfma_f32_16x16x32_bf16 v[42:45], v[168:171], v[176:179], 0
	v_mfma_f32_16x16x32_bf16 v[34:37], v[160:163], v[184:187], 0
	v_mfma_f32_16x16x32_bf16 v[26:29], v[168:171], v[184:187], 0
	v_mfma_f32_16x16x32_bf16 v[18:21], v[160:163], v[192:195], 0
	v_mfma_f32_16x16x32_bf16 v[10:13], v[168:171], v[192:195], 0
	v_mfma_f32_16x16x32_bf16 v[6:9], v[160:163], v[200:203], 0
	v_mfma_f32_16x16x32_bf16 v[2:5], v[168:171], v[200:203], 0
	v_mfma_f32_16x16x32_bf16 v[50:53], v[164:167], v[180:183], v[50:53]
	v_mfma_f32_16x16x32_bf16 v[42:45], v[172:175], v[180:183], v[42:45]
	v_mfma_f32_16x16x32_bf16 v[34:37], v[164:167], v[188:191], v[34:37]
	v_mfma_f32_16x16x32_bf16 v[26:29], v[172:175], v[188:191], v[26:29]
	v_mfma_f32_16x16x32_bf16 v[18:21], v[164:167], v[196:199], v[18:21]
	v_mfma_f32_16x16x32_bf16 v[10:13], v[172:175], v[196:199], v[10:13]
	v_mfma_f32_16x16x32_bf16 v[6:9], v[164:167], v[204:207], v[6:9]
	s_barrier
	v_mfma_f32_16x16x32_bf16 v[2:5], v[172:175], v[204:207], v[2:5]
	s_setprio 0
	s_add_i32 s6, 0, 0x18000
	s_add_i32 s7, 0, 0x1c000
	v_add_u32_e32 v156, s6, v146
	v_add_u32_e32 v172, s7, v146
	ds_read_b128 v[140:143], v156
	ds_read_b128 v[148:151], v156 offset:1024
	ds_read_b128 v[152:155], v156 offset:2048
	ds_read_b128 v[156:159], v156 offset:3072
	ds_read_b128 v[160:163], v172
	ds_read_b128 v[164:167], v172 offset:1024
	ds_read_b128 v[168:171], v172 offset:2048
	ds_read_b128 v[172:175], v172 offset:3072
	s_add_u32 s4, s36, 0x40000
	s_addc_u32 s5, s37, 0
	s_mov_b32 m0, s45
	v_lshl_add_u64 v[228:229], s[4:5], 0, v[134:135]
	ds_read_b128 v[176:179], v147 offset:32768
	ds_read_b128 v[180:183], v147 offset:33792
	ds_read_b128 v[184:187], v147 offset:34816
	ds_read_b128 v[188:191], v147 offset:35840
	ds_read_b128 v[192:195], v147 offset:36864
	ds_read_b128 v[196:199], v147 offset:37888
	ds_read_b128 v[200:203], v147 offset:38912
	ds_read_b128 v[204:207], v147 offset:39936
	global_load_lds_dwordx4 v[228:229], off
	v_lshl_add_u64 v[228:229], s[4:5], 0, v[130:131]
	s_mov_b32 m0, s46
	s_nop 0
	global_load_lds_dwordx4 v[228:229], off
	s_waitcnt vmcnt(8)
	s_waitcnt lgkmcnt(0)
	s_barrier
	s_setprio 1
	s_waitcnt lgkmcnt(0)
	v_mfma_f32_16x16x32_bf16 v[126:129], v[140:143], v[176:179], v[126:129]
	v_mfma_f32_16x16x32_bf16 v[122:125], v[152:155], v[176:179], v[122:125]
	v_mfma_f32_16x16x32_bf16 v[118:121], v[140:143], v[184:187], v[118:121]
	v_mfma_f32_16x16x32_bf16 v[110:113], v[152:155], v[184:187], v[110:113]
	v_mfma_f32_16x16x32_bf16 v[102:105], v[140:143], v[192:195], v[102:105]
	v_mfma_f32_16x16x32_bf16 v[94:97], v[152:155], v[192:195], v[94:97]
	v_mfma_f32_16x16x32_bf16 v[86:89], v[140:143], v[200:203], v[86:89]
	v_mfma_f32_16x16x32_bf16 v[78:81], v[152:155], v[200:203], v[78:81]
	v_mfma_f32_16x16x32_bf16 v[126:129], v[148:151], v[180:183], v[126:129]
	v_mfma_f32_16x16x32_bf16 v[122:125], v[156:159], v[180:183], v[122:125]
	v_mfma_f32_16x16x32_bf16 v[118:121], v[148:151], v[188:191], v[118:121]
	v_mfma_f32_16x16x32_bf16 v[110:113], v[156:159], v[188:191], v[110:113]
	v_mfma_f32_16x16x32_bf16 v[102:105], v[148:151], v[196:199], v[102:105]
	v_mfma_f32_16x16x32_bf16 v[94:97], v[156:159], v[196:199], v[94:97]
	v_mfma_f32_16x16x32_bf16 v[86:89], v[148:151], v[204:207], v[86:89]
	v_mfma_f32_16x16x32_bf16 v[78:81], v[156:159], v[204:207], v[78:81]
	s_setprio 0
	s_setprio 1
	v_mfma_f32_16x16x32_bf16 v[114:117], v[160:163], v[176:179], v[114:117]
	v_mfma_f32_16x16x32_bf16 v[106:109], v[168:171], v[176:179], v[106:109]
	v_mfma_f32_16x16x32_bf16 v[98:101], v[160:163], v[184:187], v[98:101]
	v_mfma_f32_16x16x32_bf16 v[90:93], v[168:171], v[184:187], v[90:93]
	v_mfma_f32_16x16x32_bf16 v[82:85], v[160:163], v[192:195], v[82:85]
	v_mfma_f32_16x16x32_bf16 v[74:77], v[168:171], v[192:195], v[74:77]
	v_mfma_f32_16x16x32_bf16 v[70:73], v[160:163], v[200:203], v[70:73]
	v_mfma_f32_16x16x32_bf16 v[66:69], v[168:171], v[200:203], v[66:69]
	v_mfma_f32_16x16x32_bf16 v[114:117], v[164:167], v[180:183], v[114:117]
	v_mfma_f32_16x16x32_bf16 v[106:109], v[172:175], v[180:183], v[106:109]
	v_mfma_f32_16x16x32_bf16 v[98:101], v[164:167], v[188:191], v[98:101]
	v_mfma_f32_16x16x32_bf16 v[90:93], v[172:175], v[188:191], v[90:93]
	v_mfma_f32_16x16x32_bf16 v[82:85], v[164:167], v[196:199], v[82:85]
	v_mfma_f32_16x16x32_bf16 v[74:77], v[172:175], v[196:199], v[74:77]
	v_mfma_f32_16x16x32_bf16 v[70:73], v[164:167], v[204:207], v[70:73]
	s_barrier
	v_mfma_f32_16x16x32_bf16 v[66:69], v[172:175], v[204:207], v[66:69]
	s_setprio 0
	s_add_i32 s4, s6, s38
	v_lshl_add_u64 v[208:209], v[208:209], 0, s[82:83]
	s_mov_b32 m0, s4
	ds_read_b128 v[176:179], v147 offset:49152
	ds_read_b128 v[180:183], v147 offset:50176
	ds_read_b128 v[184:187], v147 offset:51200
	ds_read_b128 v[188:191], v147 offset:52224
	ds_read_b128 v[192:195], v147 offset:53248
	ds_read_b128 v[196:199], v147 offset:54272
	ds_read_b128 v[200:203], v147 offset:55296
	ds_read_b128 v[204:207], v147 offset:56320
	global_load_lds_dwordx4 v[208:209], off
	s_add_i32 m0, s4, 0x2000
	s_add_u32 s4, s34, 0x40080
	v_lshl_add_u64 v[208:209], v[222:223], 0, s[82:83]
	s_addc_u32 s5, s35, 0
	s_add_i32 s6, s7, s38
	global_load_lds_dwordx4 v[208:209], off
	v_lshl_add_u64 v[208:209], s[4:5], 0, v[0:1]
	s_mov_b32 m0, s6
	s_nop 0
	global_load_lds_dwordx4 v[208:209], off
	v_lshl_add_u64 v[208:209], s[4:5], 0, v[132:133]
	s_add_i32 m0, s6, 0x2000
	s_nop 0
	global_load_lds_dwordx4 v[208:209], off
	v_lshl_add_u64 v[208:209], v[224:225], 0, s[82:83]
	s_mov_b32 m0, s49
	s_nop 0
	global_load_lds_dwordx4 v[208:209], off
	v_lshl_add_u64 v[208:209], v[226:227], 0, s[82:83]
	s_mov_b32 m0, s50
	s_nop 0
	global_load_lds_dwordx4 v[208:209], off
	s_waitcnt vmcnt(8)
	s_waitcnt lgkmcnt(0)
	s_barrier
	s_setprio 1
	s_waitcnt lgkmcnt(0)
	v_mfma_f32_16x16x32_bf16 v[62:65], v[140:143], v[176:179], v[62:65]
	v_mfma_f32_16x16x32_bf16 v[58:61], v[152:155], v[176:179], v[58:61]
	v_mfma_f32_16x16x32_bf16 v[54:57], v[140:143], v[184:187], v[54:57]
	v_mfma_f32_16x16x32_bf16 v[46:49], v[152:155], v[184:187], v[46:49]
	v_mfma_f32_16x16x32_bf16 v[38:41], v[140:143], v[192:195], v[38:41]
	v_mfma_f32_16x16x32_bf16 v[30:33], v[152:155], v[192:195], v[30:33]
	v_mfma_f32_16x16x32_bf16 v[22:25], v[140:143], v[200:203], v[22:25]
	v_mfma_f32_16x16x32_bf16 v[14:17], v[152:155], v[200:203], v[14:17]
	v_mfma_f32_16x16x32_bf16 v[62:65], v[148:151], v[180:183], v[62:65]
	v_mfma_f32_16x16x32_bf16 v[58:61], v[156:159], v[180:183], v[58:61]
	v_mfma_f32_16x16x32_bf16 v[54:57], v[148:151], v[188:191], v[54:57]
	v_mfma_f32_16x16x32_bf16 v[46:49], v[156:159], v[188:191], v[46:49]
	v_mfma_f32_16x16x32_bf16 v[38:41], v[148:151], v[196:199], v[38:41]
	v_mfma_f32_16x16x32_bf16 v[30:33], v[156:159], v[196:199], v[30:33]
	v_mfma_f32_16x16x32_bf16 v[22:25], v[148:151], v[204:207], v[22:25]
	v_mfma_f32_16x16x32_bf16 v[14:17], v[156:159], v[204:207], v[14:17]
	s_setprio 0
	s_setprio 1
	v_mfma_f32_16x16x32_bf16 v[50:53], v[160:163], v[176:179], v[50:53]
	v_mfma_f32_16x16x32_bf16 v[42:45], v[168:171], v[176:179], v[42:45]
	v_mfma_f32_16x16x32_bf16 v[34:37], v[160:163], v[184:187], v[34:37]
	v_mfma_f32_16x16x32_bf16 v[26:29], v[168:171], v[184:187], v[26:29]
	v_mfma_f32_16x16x32_bf16 v[18:21], v[160:163], v[192:195], v[18:21]
	v_mfma_f32_16x16x32_bf16 v[10:13], v[168:171], v[192:195], v[10:13]
	v_mfma_f32_16x16x32_bf16 v[6:9], v[160:163], v[200:203], v[6:9]
	v_mfma_f32_16x16x32_bf16 v[2:5], v[168:171], v[200:203], v[2:5]
	v_mfma_f32_16x16x32_bf16 v[50:53], v[164:167], v[180:183], v[50:53]
	v_mfma_f32_16x16x32_bf16 v[42:45], v[172:175], v[180:183], v[42:45]
	v_mfma_f32_16x16x32_bf16 v[34:37], v[164:167], v[188:191], v[34:37]
	v_mfma_f32_16x16x32_bf16 v[26:29], v[172:175], v[188:191], v[26:29]
	v_mfma_f32_16x16x32_bf16 v[18:21], v[164:167], v[196:199], v[18:21]
	v_mfma_f32_16x16x32_bf16 v[10:13], v[172:175], v[196:199], v[10:13]
	v_mfma_f32_16x16x32_bf16 v[6:9], v[164:167], v[204:207], v[6:9]
	s_barrier
	v_mfma_f32_16x16x32_bf16 v[2:5], v[172:175], v[204:207], v[2:5]
	s_setprio 0
	s_add_i32 s59, s59, 2
	s_add_u32 s30, s30, 0x100
	s_addc_u32 s31, s31, 0
	s_add_u32 s68, s68, 0x100
	s_addc_u32 s69, s69, 0
	s_cmp_gt_u32 s59, 13
